# SGU item phase 1: the fourth v vector load issued with the first three (into an idle MFMA-stage prefetch register quad) instead of 170 instructions later
# speedup vs baseline: 1.0056x; 1.0056x over previous
; #define LAS __attribute__((address_space(3)))
; __device__ __forceinline__ void sgu_item(const Params& P, LAS unsigned char* lds, int l, int item) {
;     ...
;     const int h = item & 3, chunk = item >> 2;
;     const size_t tok0 = (size_t)chunk * 128;
;     const f16* p = (const f16*)(P.ws + WS_BIG + BIG_P);
;     f16* yraw = (f16*)(P.ws + WS_BIG + BIG_YRAW);
;     LAS f16* vhT = (LAS f16*)lds;
;     LAS float* mix = (LAS float*)(lds + 128 * 272);
;     {
;         const int tk = tid >> 2, q = tid & 3;
;         const f16* vp = p + (tok0 + tk) * NIN + 2 * GW + 128 * h + 32 * q;
;         const float* gp = P.sgu_norm_g + (size_t)l * GW + 128 * h + 32 * q;
;         f32x4 v[8]; float ss = 0.f;
; #pragma unroll
;         for (int i = 0; i < 4; ++i) { const f16x8 t = *(const f16x8*)(vp + 8 * i);
; #pragma unroll
;             for (int e = 0; e < 8; ++e) { const float gv = gelu_fast((float)t[e]); v[2 * i + (e >> 2)][e & 3] = gv; ss += gv * gv; } }
; __device__ __forceinline__ void phase_moba_attn(const Params& P, LAS unsigned char* lds, int l, int qslot) {
;     ...
;         const unsigned x = y < 128u ? 896u + y : y - 128u;
;         if (tid == 0) nextx = __hip_atomic_fetch_add(qctr, 1u, __ATOMIC_RELAXED, __HIP_MEMORY_SCOPE_AGENT);
;         if (x >= 384u) {
;             if (x < 896u) sgu_item(P, lds, l, (int)(x - 384u));
.LBB0_951:
	s_andn2_b64 vcc, exec, s[0:1]
	s_cbranch_vccnz .LBB0_884
	s_addk_i32 s63, 0xfe80
	v_mov_b32_e32 v12, v0
	s_ashr_i32 s0, s63, 2
	s_ashr_i32 s1, s0, 31
	v_ashrrev_i32_e32 v30, 2, v12
	s_lshl_b64 s[0:1], s[0:1], 7
	v_ashrrev_i32_e32 v31, 31, v30
	v_lshl_add_u64 v[32:33], s[0:1], 0, v[30:31]
	v_readlane_b32 s0, v253, 0
	v_readlane_b32 s1, v253, 1
	s_waitcnt lgkmcnt(0)
	v_lshlrev_b32_e32 v2, 5, v12
	v_and_b32_e32 v34, 0x60, v2
	v_mov_b64_e32 v[4:5], s[0:1]
	v_mad_u64_u32 v[4:5], s[0:1], v32, s51, v[4:5]
	s_lshl_b32 s0, s63, 7
	s_and_b32 s18, s0, 0x180
	v_mad_i32_i24 v5, v33, s51, v5
	s_lshl_b32 s56, s18, 1
	v_lshl_add_u64 v[4:5], v[4:5], 0, s[56:57]
	v_lshlrev_b32_e32 v2, 1, v34
	v_lshl_add_u64 v[28:29], v[4:5], 0, v[2:3]
	global_load_dword v109, v[28:29], off offset:1024
	global_load_dword v207, v[28:29], off offset:1028
	global_load_dword v209, v[28:29], off offset:1032
	global_load_dword v211, v[28:29], off offset:1036
	global_load_dwordx4 v[180:183], v[28:29], off offset:1040
	global_load_dwordx4 v[214:217], v[28:29], off offset:1056
	global_load_dword v243, v[28:29], off offset:1072
	global_load_dwordx2 v[244:245], v[28:29], off offset:1076
	global_load_dword v246, v[28:29], off offset:1084
	global_load_dwordx4 v[8:11], v[28:29], off offset:2048
	global_load_dwordx4 v[24:27], v[28:29], off offset:2064
	global_load_dwordx4 v[4:7], v[28:29], off offset:2080
	global_load_dwordx4 v[110:113], v[28:29], off offset:2096
	s_lshl_b32 s0, s18, 2
	s_add_u32 s0, s52, s0
	s_addc_u32 s1, s53, 0
	v_lshlrev_b32_e32 v52, 2, v34
	v_bfe_u32 v105, v12, 5, 1
	v_readlane_b32 s64, v251, 10
	v_readlane_b32 s68, v251, 14
	v_readlane_b32 s69, v251, 15
	s_mov_b32 s19, 0
	s_mov_b64 s[8:9], -1
	s_movk_i32 s4, 0x210
	v_readlane_b32 s65, v251, 11
	v_readlane_b32 s66, v251, 12
	v_readlane_b32 s67, v251, 13
	v_readlane_b32 s70, v251, 16
	v_readlane_b32 s71, v251, 17
	v_readlane_b32 s72, v251, 18
	v_readlane_b32 s73, v251, 19
	v_readlane_b32 s74, v251, 20
	v_readlane_b32 s75, v251, 21
	v_readlane_b32 s76, v251, 22
	v_readlane_b32 s77, v251, 23
	v_readlane_b32 s78, v251, 24
	v_readlane_b32 s79, v251, 25
	s_waitcnt vmcnt(3)
	v_cvt_f32_f16_e32 v2, v8
	v_cvt_f32_f16_sdwa v13, v8 dst_sel:DWORD dst_unused:UNUSED_PAD src0_sel:WORD_1
	v_cvt_f32_f16_e32 v14, v9
	v_cvt_f32_f16_sdwa v15, v9 dst_sel:DWORD dst_unused:UNUSED_PAD src0_sel:WORD_1
	v_cvt_f32_f16_e32 v16, v10
	v_cvt_f32_f16_sdwa v19, v10 dst_sel:DWORD dst_unused:UNUSED_PAD src0_sel:WORD_1
	v_cvt_f32_f16_e32 v20, v11
	v_mul_f32_e32 v17, 0x3d372713, v2
	v_mul_f32_e32 v18, 0x3d372713, v13
	v_mul_f32_e32 v21, 0x3d372713, v14
	v_mul_f32_e32 v22, 0x3d372713, v15
	v_mul_f32_e32 v17, v17, v2
	v_mul_f32_e32 v18, v18, v13
	v_mul_f32_e32 v21, v21, v14
	v_mul_f32_e32 v22, v22, v15
	v_fma_mix_f32 v17, v17, v8, v8 op_sel_hi:[0,1,1]
	v_fma_mix_f32 v8, v18, v8, v8 op_sel:[0,1,1] op_sel_hi:[0,1,1]
	v_fma_mix_f32 v18, v21, v9, v9 op_sel_hi:[0,1,1]
	v_fma_mix_f32 v9, v22, v9, v9 op_sel:[0,1,1] op_sel_hi:[0,1,1]
	v_mul_f32_e32 v17, 0xc0135761, v17
	v_mul_f32_e32 v9, 0xc0135761, v9
	v_mul_f32_e32 v37, 0x3d372713, v16
	v_mul_f32_e32 v38, 0x3d372713, v19
	v_mul_f32_e32 v39, 0x3d372713, v20
	v_exp_f32_e32 v17, v17
	v_exp_f32_e32 v9, v9
	v_mul_f32_e32 v37, v37, v16
	v_mul_f32_e32 v38, v38, v19
	v_mul_f32_e32 v39, v39, v20
	v_fma_mix_f32 v21, v37, v10, v10 op_sel_hi:[0,1,1]
	v_fma_mix_f32 v10, v38, v10, v10 op_sel:[0,1,1] op_sel_hi:[0,1,1]
	v_fma_mix_f32 v22, v39, v11, v11 op_sel_hi:[0,1,1]
	v_mul_f32_e32 v18, 0xc0135761, v18
	v_mul_f32_e32 v10, 0xc0135761, v10
	v_mul_f32_e32 v22, 0xc0135761, v22
	v_exp_f32_e32 v18, v18
	v_exp_f32_e32 v10, v10
	v_exp_f32_e32 v22, v22
	v_add_f32_e32 v17, 1.0, v17
	v_add_f32_e32 v9, 1.0, v9
	v_rcp_f32_e32 v17, v17
	v_rcp_f32_e32 v9, v9
	v_mul_f32_e32 v8, 0xc0135761, v8
	v_exp_f32_e32 v8, v8
	v_add_f32_e32 v18, 1.0, v18
	v_add_f32_e32 v10, 1.0, v10
	v_add_f32_e32 v22, 1.0, v22
	v_cvt_f32_f16_sdwa v23, v11 dst_sel:DWORD dst_unused:UNUSED_PAD src0_sel:WORD_1
	v_rcp_f32_e32 v18, v18
	v_rcp_f32_e32 v10, v10
	v_rcp_f32_e32 v39, v22
	v_mul_f32_e32 v22, v17, v2
	v_mul_f32_e32 v17, v9, v15
	s_waitcnt vmcnt(2)
	v_cvt_f32_f16_e32 v9, v25
	v_mul_f32_e32 v21, 0xc0135761, v21
	v_exp_f32_e32 v21, v21
	v_add_f32_e32 v8, 1.0, v8
	v_cvt_f32_f16_sdwa v36, v24 dst_sel:DWORD dst_unused:UNUSED_PAD src0_sel:WORD_1
	v_mul_f32_e32 v40, 0x3d372713, v23
	v_rcp_f32_e32 v8, v8
	v_mul_f32_e32 v18, v18, v14
	v_mul_f32_e32 v14, v10, v19
	v_mul_f32_e32 v10, 0x3d372713, v9
	v_mul_f32_e32 v40, v40, v23
	v_mul_f32_e32 v10, v10, v9
	v_fma_mix_f32 v11, v40, v11, v11 op_sel:[0,1,1] op_sel_hi:[0,1,1]
	v_fma_mix_f32 v10, v10, v25, v25 op_sel_hi:[0,1,1]
	v_mul_f32_e32 v11, 0xc0135761, v11
	v_add_f32_e32 v21, 1.0, v21
	v_mul_f32_e32 v10, 0xc0135761, v10
	v_exp_f32_e32 v11, v11
	v_rcp_f32_e32 v38, v21
	v_mul_f32_e32 v21, v8, v13
	v_mul_f32_e32 v8, 0x3d372713, v36
	v_exp_f32_e32 v10, v10
	v_mul_f32_e32 v8, v8, v36
	v_fma_mix_f32 v8, v8, v24, v24 op_sel:[0,1,1] op_sel_hi:[0,1,1]
	v_mul_f32_e32 v8, 0xc0135761, v8
	v_add_f32_e32 v11, 1.0, v11
	v_exp_f32_e32 v8, v8
	v_add_f32_e32 v10, 1.0, v10
	v_rcp_f32_e32 v11, v11
	v_rcp_f32_e32 v10, v10
	v_add_f32_e32 v8, 1.0, v8
	v_rcp_f32_e32 v8, v8
	v_mul_f32_e32 v15, v11, v23
	v_cvt_f32_f16_sdwa v11, v25 dst_sel:DWORD dst_unused:UNUSED_PAD src0_sel:WORD_1
	v_mul_f32_e32 v19, v10, v9
	v_cvt_f32_f16_e32 v9, v26
	v_mul_f32_e32 v2, v39, v20
	v_mul_f32_e32 v20, v8, v36
	v_mul_f32_e32 v8, 0x3d372713, v11
	v_mul_f32_e32 v10, 0x3d372713, v9
	v_mul_f32_e32 v8, v8, v11
	v_mul_f32_e32 v10, v10, v9
	v_fma_mix_f32 v8, v8, v25, v25 op_sel:[0,1,1] op_sel_hi:[0,1,1]
	v_fma_mix_f32 v10, v10, v26, v26 op_sel_hi:[0,1,1]
; __device__ __forceinline__ void sgu_item(const Params& P, LAS unsigned char* lds, int l, int item) {
;     ...
;         for (int i = 0; i < 4; ++i) { const f16x8 t = *(const f16x8*)(vp + 8 * i);
; #pragma unroll
;             for (int e = 0; e < 8; ++e) { const float gv = gelu_fast((float)t[e]); v[2 * i + (e >> 2)][e & 3] = gv; ss += gv * gv; } }
;         ss += __shfl_xor(ss, 1); ss += __shfl_xor(ss, 2);
;         const float rstd = 1.0f / sqrtf(ss * (1.0f / HD) + EPS);
	v_mul_f32_e32 v8, 0xc0135761, v8
	v_mul_f32_e32 v10, 0xc0135761, v10
	v_exp_f32_e32 v8, v8
	v_exp_f32_e32 v10, v10
	v_cvt_f32_f16_e32 v35, v24
	v_cvt_f32_f16_sdwa v25, v26 dst_sel:DWORD dst_unused:UNUSED_PAD src0_sel:WORD_1
	v_add_f32_e32 v8, 1.0, v8
	v_add_f32_e32 v10, 1.0, v10
	v_mul_f32_e32 v41, 0x3d372713, v35
	v_rcp_f32_e32 v8, v8
	v_rcp_f32_e32 v10, v10
	v_mul_f32_e32 v41, v41, v35
	v_fma_mix_f32 v37, v41, v24, v24 op_sel_hi:[0,1,1]
	v_mul_f32_e32 v37, 0xc0135761, v37
	v_exp_f32_e32 v37, v37
	v_mul_f32_e32 v24, v8, v11
	v_mul_f32_e32 v23, v10, v9
	v_mul_f32_e32 v8, 0x3d372713, v25
	v_cvt_f32_f16_e32 v9, v27
	v_mul_f32_e32 v8, v8, v25
	v_fma_mix_f32 v8, v8, v26, v26 op_sel:[0,1,1] op_sel_hi:[0,1,1]
	v_mul_f32_e32 v8, 0xc0135761, v8
	v_add_f32_e32 v37, 1.0, v37
	v_exp_f32_e32 v8, v8
	v_mul_f32_e32 v10, 0x3d372713, v9
	v_rcp_f32_e32 v37, v37
	v_mul_f32_e32 v10, v10, v9
	v_fma_mix_f32 v10, v10, v27, v27 op_sel_hi:[0,1,1]
	v_mul_f32_e32 v10, 0xc0135761, v10
	v_exp_f32_e32 v10, v10
	v_add_f32_e32 v8, 1.0, v8
	v_mul_f32_e32 v13, v37, v35
	v_rcp_f32_e32 v8, v8
	v_cvt_f32_f16_sdwa v35, v27 dst_sel:DWORD dst_unused:UNUSED_PAD src0_sel:WORD_1
	v_add_f32_e32 v10, 1.0, v10
	v_rcp_f32_e32 v10, v10
	v_mul_f32_e32 v26, v8, v25
	v_mul_f32_e32 v8, 0x3d372713, v35
	v_mul_f32_e32 v8, v8, v35
	v_fma_mix_f32 v8, v8, v27, v27 op_sel:[0,1,1] op_sel_hi:[0,1,1]
	v_mul_f32_e32 v8, 0xc0135761, v8
	v_mul_f32_e32 v25, v10, v9
	v_exp_f32_e32 v27, v8
	s_nop 0
	s_waitcnt vmcnt(1)
	v_cvt_f32_f16_e32 v36, v4
	v_mul_f32_e32 v16, v38, v16
	v_add_f32_e32 v27, 1.0, v27
	v_rcp_f32_e32 v27, v27
	v_mul_f32_e32 v37, 0x3d372713, v36
	v_mul_f32_e32 v37, v37, v36
	v_fma_mix_f32 v37, v37, v4, v4 op_sel_hi:[0,1,1]
	v_mul_f32_e32 v37, 0xc0135761, v37
	v_exp_f32_e32 v37, v37
	v_mul_f32_e32 v27, v27, v35
	v_cvt_f32_f16_sdwa v35, v4 dst_sel:DWORD dst_unused:UNUSED_PAD src0_sel:WORD_1
	v_mul_f32_e32 v40, v21, v21
	v_add_f32_e32 v37, 1.0, v37
	v_rcp_f32_e32 v37, v37
	v_mul_f32_e32 v38, 0x3d372713, v35
	v_mul_f32_e32 v38, v38, v35
	v_fma_mix_f32 v4, v38, v4, v4 op_sel:[0,1,1] op_sel_hi:[0,1,1]
	v_mul_f32_e32 v4, 0xc0135761, v4
	v_exp_f32_e32 v4, v4
	v_mul_f32_e32 v56, v37, v36
	v_cvt_f32_f16_e32 v36, v5
	v_fmac_f32_e32 v40, v22, v22
	v_add_f32_e32 v4, 1.0, v4
	v_rcp_f32_e32 v4, v4
	v_mul_f32_e32 v37, 0x3d372713, v36
	v_mul_f32_e32 v37, v37, v36
	v_fma_mix_f32 v37, v37, v5, v5 op_sel_hi:[0,1,1]
	v_mul_f32_e32 v37, 0xc0135761, v37
	v_exp_f32_e32 v37, v37
	v_mul_f32_e32 v35, v4, v35
	v_cvt_f32_f16_sdwa v4, v5 dst_sel:DWORD dst_unused:UNUSED_PAD src0_sel:WORD_1
	v_fmac_f32_e32 v40, v18, v18
	v_add_f32_e32 v37, 1.0, v37
	v_rcp_f32_e32 v37, v37
	v_mul_f32_e32 v38, 0x3d372713, v4
	v_mul_f32_e32 v38, v38, v4
	v_fma_mix_f32 v5, v38, v5, v5 op_sel:[0,1,1] op_sel_hi:[0,1,1]
	v_mul_f32_e32 v5, 0xc0135761, v5
	v_exp_f32_e32 v5, v5
	v_mul_f32_e32 v57, v37, v36
	v_cvt_f32_f16_e32 v36, v6
	v_fmac_f32_e32 v40, v17, v17
	v_add_f32_e32 v5, 1.0, v5
	v_rcp_f32_e32 v5, v5
	v_mul_f32_e32 v37, 0x3d372713, v36
	v_mul_f32_e32 v37, v37, v36
	v_fma_mix_f32 v37, v37, v6, v6 op_sel_hi:[0,1,1]
	v_mul_f32_e32 v37, 0xc0135761, v37
	v_exp_f32_e32 v37, v37
	v_mul_f32_e32 v58, v5, v4
	v_cvt_f32_f16_sdwa v4, v6 dst_sel:DWORD dst_unused:UNUSED_PAD src0_sel:WORD_1
	v_fmac_f32_e32 v40, v16, v16
	v_add_f32_e32 v5, 1.0, v37
	v_rcp_f32_e32 v5, v5
	v_mul_f32_e32 v37, 0x3d372713, v4
	v_mul_f32_e32 v37, v37, v4
	v_fma_mix_f32 v6, v37, v6, v6 op_sel:[0,1,1] op_sel_hi:[0,1,1]
	v_mul_f32_e32 v6, 0xc0135761, v6
	v_exp_f32_e32 v6, v6
	v_mul_f32_e32 v59, v5, v36
	v_cvt_f32_f16_e32 v5, v7
	v_fmac_f32_e32 v40, v14, v14
	v_add_f32_e32 v6, 1.0, v6
	v_rcp_f32_e32 v6, v6
	v_mul_f32_e32 v36, 0x3d372713, v5
	v_mul_f32_e32 v36, v36, v5
	v_fma_mix_f32 v36, v36, v7, v7 op_sel_hi:[0,1,1]
	v_mul_f32_e32 v36, 0xc0135761, v36
	v_exp_f32_e32 v36, v36
	v_mul_f32_e32 v60, v6, v4
	v_cvt_f32_f16_sdwa v4, v7 dst_sel:DWORD dst_unused:UNUSED_PAD src0_sel:WORD_1
	v_fmac_f32_e32 v40, v2, v2
	v_add_f32_e32 v6, 1.0, v36
	v_rcp_f32_e32 v6, v6
	v_mul_f32_e32 v36, 0x3d372713, v4
	v_mul_f32_e32 v36, v36, v4
	v_fma_mix_f32 v7, v36, v7, v7 op_sel:[0,1,1] op_sel_hi:[0,1,1]
	v_mul_f32_e32 v7, 0xc0135761, v7
	v_exp_f32_e32 v7, v7
	v_mul_f32_e32 v61, v6, v5
	s_waitcnt vmcnt(0)
	v_mov_b32_e32 v8, v110
	v_mov_b32_e32 v9, v111
	v_mov_b32_e32 v10, v112
	v_mov_b32_e32 v11, v113
	v_cvt_f32_f16_e32 v5, v8
	v_fmac_f32_e32 v40, v15, v15
	v_add_f32_e32 v6, 1.0, v7
	v_rcp_f32_e32 v6, v6
	v_mul_f32_e32 v7, 0x3d372713, v5
	v_mul_f32_e32 v7, v7, v5
	v_fma_mix_f32 v7, v7, v8, v8 op_sel_hi:[0,1,1]
	v_mul_f32_e32 v7, 0xc0135761, v7
	v_exp_f32_e32 v7, v7
	v_mul_f32_e32 v62, v6, v4
	v_cvt_f32_f16_sdwa v4, v8 dst_sel:DWORD dst_unused:UNUSED_PAD src0_sel:WORD_1
	v_fmac_f32_e32 v40, v13, v13
	v_add_f32_e32 v6, 1.0, v7
	v_rcp_f32_e32 v6, v6
	v_mul_f32_e32 v7, 0x3d372713, v4
	v_mul_f32_e32 v7, v7, v4
	v_fma_mix_f32 v7, v7, v8, v8 op_sel:[0,1,1] op_sel_hi:[0,1,1]
	v_mul_f32_e32 v7, 0xc0135761, v7
	v_exp_f32_e32 v7, v7
	v_mul_f32_e32 v63, v6, v5
	v_cvt_f32_f16_e32 v5, v9
	v_cvt_f32_f16_sdwa v8, v10 dst_sel:DWORD dst_unused:UNUSED_PAD src0_sel:WORD_1
	v_add_f32_e32 v6, 1.0, v7
	v_rcp_f32_e32 v6, v6
	v_mul_f32_e32 v7, 0x3d372713, v5
	v_mul_f32_e32 v7, v7, v5
	v_fma_mix_f32 v7, v7, v9, v9 op_sel_hi:[0,1,1]
	v_mul_f32_e32 v7, 0xc0135761, v7
	v_exp_f32_e32 v7, v7
	v_mul_f32_e32 v64, v6, v4
	v_cvt_f32_f16_sdwa v4, v9 dst_sel:DWORD dst_unused:UNUSED_PAD src0_sel:WORD_1
	v_fmac_f32_e32 v40, v20, v20
	v_add_f32_e32 v6, 1.0, v7
	v_rcp_f32_e32 v6, v6
	v_mul_f32_e32 v7, 0x3d372713, v4
	v_mul_f32_e32 v7, v7, v4
	v_fma_mix_f32 v7, v7, v9, v9 op_sel:[0,1,1] op_sel_hi:[0,1,1]
	v_mul_f32_e32 v7, 0xc0135761, v7
; __device__ __forceinline__ void sgu_item(const Params& P, LAS unsigned char* lds, int l, int item) {
;     ...
;         for (int i = 0; i < 4; ++i) { const f16x8 t = *(const f16x8*)(vp + 8 * i);
; #pragma unroll
;             for (int e = 0; e < 8; ++e) { const float gv = gelu_fast((float)t[e]); v[2 * i + (e >> 2)][e & 3] = gv; ss += gv * gv; } }
;         ss += __shfl_xor(ss, 1); ss += __shfl_xor(ss, 2);
;         const float rstd = 1.0f / sqrtf(ss * (1.0f / HD) + EPS);
; #pragma unroll
;         for (int i = 0; i < 8; ++i) { const f32x4 gg = *(const f32x4*)(gp + 4 * i); const f32x4 y = (v[i] * rstd) * gg;
; #pragma unroll
;             for (int e = 0; e < 4; ++e) vhT[(32 * q + 4 * i + e) * 136 + tk] = (f16)y[e]; }
	v_exp_f32_e32 v7, v7
	v_mul_f32_e32 v65, v6, v5
	v_cvt_f32_f16_e32 v5, v10
	v_cvt_f32_f16_e32 v9, v11
	v_add_f32_e32 v6, 1.0, v7
	v_rcp_f32_e32 v6, v6
	v_mul_f32_e32 v7, 0x3d372713, v5
	v_mul_f32_e32 v7, v7, v5
	v_fma_mix_f32 v7, v7, v10, v10 op_sel_hi:[0,1,1]
	v_mul_f32_e32 v7, 0xc0135761, v7
	v_exp_f32_e32 v7, v7
	v_mul_f32_e32 v66, v6, v4
	v_mul_f32_e32 v6, 0x3d372713, v8
	v_mul_f32_e32 v6, v6, v8
	v_fma_mix_f32 v6, v6, v10, v10 op_sel:[0,1,1] op_sel_hi:[0,1,1]
	v_add_f32_e32 v4, 1.0, v7
	v_mul_f32_e32 v6, 0xc0135761, v6
	v_rcp_f32_e32 v4, v4
	v_exp_f32_e32 v6, v6
	v_fmac_f32_e32 v40, v19, v19
	v_fmac_f32_e32 v40, v24, v24
	v_mul_f32_e32 v67, v4, v5
	v_add_f32_e32 v4, 1.0, v6
	v_rcp_f32_e32 v10, v4
	v_mul_f32_e32 v4, 0x3d372713, v9
	v_mul_f32_e32 v4, v4, v9
	v_fma_mix_f32 v4, v4, v11, v11 op_sel_hi:[0,1,1]
	v_mul_f32_e32 v4, 0xc0135761, v4
	v_exp_f32_e32 v41, v4
	global_load_dwordx4 v[4:7], v52, s[0:1] offset:16
	global_load_dwordx4 v[36:39], v52, s[0:1]
	v_fmac_f32_e32 v40, v23, v23
	v_fmac_f32_e32 v40, v26, v26
	v_cvt_f32_f16_sdwa v42, v11 dst_sel:DWORD dst_unused:UNUSED_PAD src0_sel:WORD_1
	v_fmac_f32_e32 v40, v25, v25
	v_fmac_f32_e32 v40, v27, v27
	v_fmac_f32_e32 v40, v56, v56
	v_fmac_f32_e32 v40, v35, v35
	v_mul_f32_e32 v43, 0x3d372713, v42
	v_fmac_f32_e32 v40, v57, v57
	v_mul_f32_e32 v43, v43, v42
	v_fmac_f32_e32 v40, v58, v58
	v_fma_mix_f32 v11, v43, v11, v11 op_sel:[0,1,1] op_sel_hi:[0,1,1]
	v_fmac_f32_e32 v40, v59, v59
	v_mul_f32_e32 v11, 0xc0135761, v11
	v_fmac_f32_e32 v40, v60, v60
	v_exp_f32_e32 v11, v11
	v_fmac_f32_e32 v40, v61, v61
	v_mul_f32_e32 v68, v10, v8
	v_add_f32_e32 v8, 1.0, v41
	v_fmac_f32_e32 v40, v62, v62
	v_rcp_f32_e32 v8, v8
	v_fmac_f32_e32 v40, v63, v63
	v_fmac_f32_e32 v40, v64, v64
	v_add_f32_e32 v10, 1.0, v11
	v_fmac_f32_e32 v40, v65, v65
	v_rcp_f32_e32 v10, v10
	v_fmac_f32_e32 v40, v66, v66
	v_mul_f32_e32 v69, v8, v9
	v_and_b32_e32 v9, 64, v238
	v_fmac_f32_e32 v40, v67, v67
	v_xor_b32_e32 v8, 1, v238
	v_add_u32_e32 v9, 64, v9
	v_fmac_f32_e32 v40, v68, v68
	v_cmp_lt_i32_e32 vcc, v8, v9
	v_fmac_f32_e32 v40, v69, v69
	v_mul_f32_e32 v70, v10, v42
	v_cndmask_b32_e32 v8, v238, v8, vcc
	v_fmac_f32_e32 v40, v70, v70
	v_lshlrev_b32_e32 v8, 2, v8
	ds_bpermute_b32 v8, v8, v40
	s_waitcnt lgkmcnt(0)
	v_add_f32_e32 v40, v40, v8
	v_xor_b32_e32 v8, 2, v238
	v_cmp_lt_i32_e32 vcc, v8, v9
	s_nop 1
	v_cndmask_b32_e32 v8, v238, v8, vcc
	v_lshlrev_b32_e32 v8, 2, v8
	ds_bpermute_b32 v41, v8, v40
	global_load_dwordx4 v[8:11], v52, s[0:1] offset:32
	s_waitcnt lgkmcnt(0)
	v_add_f32_e32 v40, v40, v41
	v_fmamk_f32 v40, v40, 0x3c000000, v234
	v_mul_f32_e32 v41, 0x4f800000, v40
	v_cmp_gt_f32_e32 vcc, s83, v40
	s_nop 1
	v_cndmask_b32_e32 v44, v40, v41, vcc
	v_sqrt_f32_e32 v45, v44
	global_load_dwordx4 v[40:43], v52, s[0:1] offset:48
	v_add_u32_e32 v46, -1, v45
	v_fma_f32 v47, -v46, v45, v44
	v_cmp_ge_f32_e64 s[46:47], 0, v47
	v_add_u32_e32 v47, 1, v45
	s_nop 0
	v_cndmask_b32_e64 v46, v45, v46, s[46:47]
	v_fma_f32 v45, -v47, v45, v44
	v_cmp_lt_f32_e64 s[46:47], 0, v45
	s_nop 1
	v_cndmask_b32_e64 v45, v46, v47, s[46:47]
	v_mul_f32_e32 v46, 0x37800000, v45
	v_cndmask_b32_e32 v45, v45, v46, vcc
	v_cmp_class_f32_e32 vcc, v44, v235
	s_nop 1
	v_cndmask_b32_e32 v53, v45, v44, vcc
	v_div_scale_f32 v54, s[2:3], v53, v53, 1.0
	v_rcp_f32_e32 v55, v54
	v_div_scale_f32 v71, vcc, 1.0, v53, 1.0
	v_readfirstlane_b32 s2, v12
	v_fma_f32 v44, -v54, v55, 1.0
	v_fmac_f32_e32 v55, v44, v55
	global_load_dwordx4 v[44:47], v52, s[0:1] offset:80
	global_load_dwordx4 v[48:51], v52, s[0:1] offset:64
	v_mul_f32_e32 v72, v71, v55
	v_fma_f32 v73, -v54, v72, v71
	v_fmac_f32_e32 v72, v73, v55
	v_fma_f32 v54, -v54, v72, v71
	v_div_fmas_f32 v54, v54, v55, v72
	v_div_fixup_f32 v71, v54, v53, 1.0
	v_mul_f32_e32 v22, v22, v71
	v_lshlrev_b32_e32 v53, 1, v30
	s_waitcnt vmcnt(4)
	v_fma_mixlo_f16 v22, v36, v22, 0
	v_mul_u32_u24_e32 v36, 0x110, v34
	v_mul_f32_e32 v21, v21, v71
	v_mul_f32_e32 v18, v18, v71
	v_mul_f32_e32 v17, v17, v71
	v_add3_u32 v72, 0, v53, v36
	v_fma_mixlo_f16 v21, v37, v21, 0
	v_fma_mixlo_f16 v18, v38, v18, 0
	v_fma_mixlo_f16 v17, v39, v17, 0
	ds_write_b16 v72, v22
	ds_write_b16 v72, v21 offset:272
	ds_write_b16 v72, v18 offset:544
	ds_write_b16 v72, v17 offset:816
	global_load_dwordx4 v[36:39], v52, s[0:1] offset:112
	s_nop 0
	global_load_dwordx4 v[52:55], v52, s[0:1] offset:96
	v_mul_f32_e32 v2, v2, v71
	v_fma_mixlo_f16 v2, v6, v2, 0
	ds_write_b16 v72, v2 offset:1632
	v_mul_f32_e32 v2, v15, v71
	v_fma_mixlo_f16 v2, v7, v2, 0
	ds_write_b16 v72, v2 offset:1904
	v_mul_f32_e32 v2, v13, v71
	v_mul_f32_e32 v16, v16, v71
	s_cmpk_gt_u32 s2, 0xff
	v_fma_mixlo_f16 v4, v4, v16, 0
	s_cselect_b64 s[0:1], -1, 0
	s_lshr_b32 s2, s2, 1
	ds_write_b16 v72, v4 offset:1088
	v_mul_f32_e32 v4, v14, v71
	s_and_b32 s2, s2, 0x60
	v_fma_mixlo_f16 v4, v5, v4, 0
	ds_write_b16 v72, v4 offset:1360
	s_waitcnt vmcnt(5)
; #define LAS __attribute__((address_space(3)))
; __device__ __forceinline__ void sgu_item(const Params& P, LAS unsigned char* lds, int l, int item) {
;     ...
;         for (int i = 0; i < 8; ++i) { const f32x4 gg = *(const f32x4*)(gp + 4 * i); const f32x4 y = (v[i] * rstd) * gg;
; #pragma unroll
;             for (int e = 0; e < 4; ++e) vhT[(32 * q + 4 * i + e) * 136 + tk] = (f16)y[e]; }
;     }
;     __syncthreads();
;     const int cb = wave & 3, pr = wave >> 2;
; #pragma unroll 1
;     for (int ti = 0; ti < 2; ++ti) {
;         const int tb = pr ? (1 + ti) : (3 * ti), t = 32 * tb + ln;
;         f32x16 acc;
; #pragma unroll
;         for (int r = 0; r < 16; ++r) acc[r] = 0.f;
;         const float* wrow = P.sgu_w + (((size_t)l * NH + h) * 128 + t) * 128 + 8 * hf;
;         const LAS f16* vrow = vhT + (32 * cb + ln) * 136 + 8 * hf;
; #pragma unroll
;         for (int st = 0; st < 8; ++st) if (st < 2 * (tb + 1)) {
;             const f32x4 w0 = *(const f32x4*)(wrow + 16 * st), w1 = *(const f32x4*)(wrow + 16 * st + 4);
;             f16x8 wf;
; #pragma unroll
;             for (int e = 0; e < 4; ++e) { const int s0 = 16 * st + 8 * hf + e; wf[e] = (s0 <= t) ? (f16)w0[e] : (f16)0.f; wf[4 + e] = (s0 + 4 <= t) ? (f16)w1[e] : (f16)0.f; }
	v_fma_mixlo_f16 v2, v8, v2, 0
	ds_write_b16 v72, v2 offset:2176
	v_mul_f32_e32 v2, v20, v71
	v_fma_mixlo_f16 v2, v9, v2, 0
	ds_write_b16 v72, v2 offset:2448
	v_mul_f32_e32 v2, v19, v71
	v_fma_mixlo_f16 v2, v10, v2, 0
	ds_write_b16 v72, v2 offset:2720
	v_mul_f32_e32 v2, v24, v71
	v_fma_mixlo_f16 v2, v11, v2, 0
	ds_write_b16 v72, v2 offset:2992
	v_mul_f32_e32 v2, v23, v71
	s_waitcnt vmcnt(4)
	v_fma_mixlo_f16 v2, v40, v2, 0
	ds_write_b16 v72, v2 offset:3264
	v_mul_f32_e32 v2, v26, v71
	v_fma_mixlo_f16 v2, v41, v2, 0
	ds_write_b16 v72, v2 offset:3536
	v_mul_f32_e32 v2, v25, v71
	v_fma_mixlo_f16 v2, v42, v2, 0
	ds_write_b16 v72, v2 offset:3808
	v_mul_f32_e32 v2, v27, v71
	v_fma_mixlo_f16 v2, v43, v2, 0
	ds_write_b16 v72, v2 offset:4080
	v_mul_f32_e32 v2, v56, v71
	v_lshlrev_b32_e32 v4, 4, v105
	v_lshlrev_b32_e32 v40, 3, v105
	s_or_b32 s3, s30, s18
	v_or_b32_e32 v43, 4, v40
	v_or_b32_e32 v56, 23, v40
	v_or_b32_e32 v73, 64, v40
	v_or_b32_e32 v74, 0x44, v40
	v_or_b32_e32 v75, 0x41, v40
	v_or_b32_e32 v76, 0x45, v40
	v_or_b32_e32 v77, 0x42, v40
	v_or_b32_e32 v78, 0x46, v40
	v_or_b32_e32 v79, 0x43, v40
	v_or_b32_e32 v80, 0x47, v40
	v_or_b32_e32 v81, 0x50, v40
	v_or_b32_e32 v82, 0x54, v40
	v_or_b32_e32 v83, 0x51, v40
	s_waitcnt vmcnt(2)
	v_fma_mixlo_f16 v2, v48, v2, 0
	ds_write_b16 v72, v2 offset:4352
	v_mul_f32_e32 v2, v35, v71
	v_fma_mixlo_f16 v2, v49, v2, 0
	ds_write_b16 v72, v2 offset:4624
	v_mul_f32_e32 v2, v57, v71
	v_fma_mixlo_f16 v2, v50, v2, 0
	ds_write_b16 v72, v2 offset:4896
	v_mul_f32_e32 v2, v58, v71
	v_fma_mixlo_f16 v2, v51, v2, 0
	ds_write_b16 v72, v2 offset:5168
	v_mul_f32_e32 v2, v59, v71
	v_fma_mixlo_f16 v2, v44, v2, 0
	ds_write_b16 v72, v2 offset:5440
	v_mul_f32_e32 v2, v60, v71
	v_fma_mixlo_f16 v2, v45, v2, 0
	ds_write_b16 v72, v2 offset:5712
	v_mul_f32_e32 v2, v61, v71
	v_fma_mixlo_f16 v2, v46, v2, 0
	ds_write_b16 v72, v2 offset:5984
	v_mul_f32_e32 v2, v62, v71
	v_fma_mixlo_f16 v2, v47, v2, 0
	ds_write_b16 v72, v2 offset:6256
	v_mul_f32_e32 v2, v63, v71
	s_waitcnt vmcnt(0)
	v_fma_mixlo_f16 v2, v52, v2, 0
	ds_write_b16 v72, v2 offset:6528
	v_mul_f32_e32 v2, v64, v71
	v_fma_mixlo_f16 v2, v53, v2, 0
	ds_write_b16 v72, v2 offset:6800
	v_mul_f32_e32 v2, v65, v71
	v_fma_mixlo_f16 v2, v54, v2, 0
	ds_write_b16 v72, v2 offset:7072
	v_mul_f32_e32 v2, v66, v71
	v_fma_mixlo_f16 v2, v55, v2, 0
	ds_write_b16 v72, v2 offset:7344
	v_mul_f32_e32 v2, v67, v71
	v_fma_mixlo_f16 v2, v36, v2, 0
	ds_write_b16 v72, v2 offset:7616
	v_mul_f32_e32 v2, v68, v71
	v_fma_mixlo_f16 v2, v37, v2, 0
	ds_write_b16 v72, v2 offset:7888
	v_mul_f32_e32 v2, v69, v71
	v_fma_mixlo_f16 v2, v38, v2, 0
	ds_write_b16 v72, v2 offset:8160
	v_mul_f32_e32 v2, v70, v71
	v_fma_mixlo_f16 v2, v39, v2, 0
	v_and_b32_e32 v35, 31, v12
	ds_write_b16 v72, v2 offset:8432
	v_or_b32_e32 v2, s2, v35
	v_mul_u32_u24_e32 v2, 0x110, v2
	s_lshl_b32 s2, s2, 2
	v_add3_u32 v41, 0, v2, v4
	s_add_i32 s2, s2, 0
	v_lshlrev_b32_e32 v2, 5, v105
	v_add_u32_e32 v42, s2, v4
	v_or_b32_e32 v44, 5, v40
	v_or_b32_e32 v45, 2, v40
	v_or_b32_e32 v46, 6, v40
	v_or_b32_e32 v47, 3, v40
	v_or_b32_e32 v48, 7, v40
	v_or_b32_e32 v49, 16, v40
	v_or_b32_e32 v50, 20, v40
	v_or_b32_e32 v51, 17, v40
	v_or_b32_e32 v52, 21, v40
	v_or_b32_e32 v53, 18, v40
	v_or_b32_e32 v54, 22, v40
	v_or_b32_e32 v55, 19, v40
	v_or_b32_e32 v57, 32, v40
	v_or_b32_e32 v58, 36, v40
	v_or_b32_e32 v59, 33, v40
	v_or_b32_e32 v60, 37, v40
	v_or_b32_e32 v61, 34, v40
	v_or_b32_e32 v62, 38, v40
	v_or_b32_e32 v63, 35, v40
	v_or_b32_e32 v64, 39, v40
	v_or_b32_e32 v65, 48, v40
	v_or_b32_e32 v66, 52, v40
	v_or_b32_e32 v67, 49, v40
	v_or_b32_e32 v68, 53, v40
	v_or_b32_e32 v69, 50, v40
	v_or_b32_e32 v70, 54, v40
	v_or_b32_e32 v71, 51, v40
	v_or_b32_e32 v72, 55, v40
	v_or_b32_e32 v84, 0x55, v40
	v_or_b32_e32 v85, 0x52, v40
	v_or_b32_e32 v86, 0x56, v40
	v_or_b32_e32 v87, 0x53, v40
	v_or_b32_e32 v88, 0x57, v40
	v_or_b32_e32 v89, 0x60, v40
	v_or_b32_e32 v90, 0x64, v40
	v_or_b32_e32 v91, 0x61, v40
	v_or_b32_e32 v92, 0x65, v40
	v_or_b32_e32 v93, 0x62, v40
	v_or_b32_e32 v94, 0x66, v40
	v_or_b32_e32 v95, 0x63, v40
	v_or_b32_e32 v96, 0x67, v40
	v_or_b32_e32 v97, 0x70, v40
	v_or_b32_e32 v98, 0x74, v40
	v_or_b32_e32 v99, 0x71, v40
	v_or_b32_e32 v100, 0x75, v40
	v_or_b32_e32 v101, 0x72, v40
	v_or_b32_e32 v102, 0x76, v40
	v_or_b32_e32 v103, 0x73, v40
	v_or_b32_e32 v104, 0x77, v40
	v_lshl_add_u64 v[36:37], s[68:69], 0, v[2:3]
	s_waitcnt lgkmcnt(0)
	s_barrier
	s_branch .LBB0_954
